# v7 + dilated-attention P.V block: row-sum adds and bf16 packing moved into the P.V MFMA gaps, V fragments double-buffered with counted lgkmcnt
# baseline (speedup 1.0000x reference)
; __device__ __forceinline__ float fast_exp2(float x) { return __builtin_amdgcn_exp2f(x); }
; __device__ __forceinline__ float xhalf_max(float x) { auto rr = __builtin_amdgcn_permlane32_swap(__float_as_uint(x), __float_as_uint(x), false, false); return fmaxf(__uint_as_float(rr[0]), __uint_as_float(rr[1])); }
; template <int D, int DV, int MODE, bool HASBIAS, bool JOINT, bool DEFER, class KA, class VA, class PF, class BF, class VF, class NM, class WS, class CB> ...
;     ...
;                     float mx0 = fmaxf(fmaxf(s[0], s[1]), s[2]), mx1 = fmaxf(fmaxf(s[3], s[4]), s[5]);
;                     mx0 = fmaxf(fmaxf(mx0, s[6]), s[7]); mx1 = fmaxf(fmaxf(mx1, s[8]), s[9]); mx0 = fmaxf(fmaxf(mx0, s[10]), s[11]); mx1 = fmaxf(fmaxf(mx1, s[12]), s[13]);
;                     float mx = fmaxf(fmaxf(mx0, mx1), fmaxf(s[14], s[15]));
;                     mx = xhalf_max(mx);
;                     const bool grow = __any(mx > m + RESC_THR);
;                     const float mn = grow ? fmaxf(m, mx) : m; float sum = 0.f;
;                     if (masked) {
; #pragma unroll
;                         for (int v = 0; v < 16; ++v) { const float p = s[v] > -1e29f ? fast_exp2(s[v] - mn) : 0.f; s[v] = p; sum += p; }
;                     } else {
; #pragma unroll
;                         for (int v = 0; v < 16; ++v) { const float p = fast_exp2(s[v] - mn); s[v] = p; sum += p; }
;                     }
.LBB0_319:
	v_max3_f32 v1, v82, v83, v96
	v_max3_f32 v2, v97, v86, v87
	v_max3_f32 v1, v1, v88, v89
	v_max3_f32 v2, v2, v90, v91
	v_max_f32_e32 v4, v85, v85
	v_max_f32_e32 v5, v84, v84
	v_max3_f32 v1, v1, v92, v93
	v_max3_f32 v2, v2, v94, v95
	v_max_f32_e32 v4, v5, v4
	v_max3_f32 v1, v1, v2, v4
	v_mov_b32_e32 v2, v1
	s_nop 1
	v_permlane32_swap_b32_e32 v1, v2
	v_max_f32_e32 v2, v2, v2
	v_max_f32_e32 v1, v1, v1
	v_max_f32_e32 v1, v1, v2
	v_add_f32_e32 v2, 0x40c00000, v232
	v_cmp_gt_f32_e32 vcc, v1, v2
	s_cmp_lg_u64 vcc, 0
	s_cselect_b64 s[8:9], -1, 0
	s_cmp_eq_u64 vcc, 0
	v_max_f32_e32 v2, v232, v232
	s_cselect_b64 vcc, -1, 0
	v_max_f32_e32 v234, v2, v1
	v_cndmask_b32_e32 v233, v234, v232, vcc
	v_sub_f32_e32 v1, v82, v233
	v_sub_f32_e32 v2, v83, v233
	v_sub_f32_e32 v4, v96, v233
	v_sub_f32_e32 v5, v97, v233
	v_sub_f32_e32 v6, v86, v233
	v_sub_f32_e32 v7, v87, v233
	v_sub_f32_e32 v8, v88, v233
	v_sub_f32_e32 v9, v89, v233
	v_sub_f32_e32 v10, v90, v233
	v_sub_f32_e32 v11, v91, v233
	v_sub_f32_e32 v12, v92, v233
	v_sub_f32_e32 v13, v93, v233
	v_sub_f32_e32 v14, v94, v233
	v_sub_f32_e32 v15, v95, v233
	v_sub_f32_e32 v176, v84, v233
	v_sub_f32_e32 v177, v85, v233
	v_exp_f32_e32 v16, v1
	v_exp_f32_e32 v1, v2
	v_exp_f32_e32 v2, v4
	v_exp_f32_e32 v17, v5
	v_exp_f32_e32 v4, v6
	v_exp_f32_e32 v5, v7
	v_exp_f32_e32 v6, v8
	v_exp_f32_e32 v7, v9
	v_exp_f32_e32 v8, v10
	v_exp_f32_e32 v9, v11
	v_exp_f32_e32 v10, v12
	v_exp_f32_e32 v11, v13
	v_exp_f32_e32 v12, v14
	v_exp_f32_e32 v13, v15
	v_exp_f32_e32 v14, v176
	v_exp_f32_e32 v15, v177
	s_mov_b64 s[16:17], -1
	s_andn2_b64 vcc, exec, s[10:11]
	s_cbranch_vccnz .LBB0_333
	s_cbranch_execz .LBB0_334

; __device__ __forceinline__ unsigned cvt_pk_bf16(float lo, float hi) { unsigned r; asm volatile("v_cvt_pk_bf16_f32 %0, %1, %2" : "=v"(r) : "v"(lo), "v"(hi)); return r; }
; #define LAS __attribute__((address_space(3)))
; template <int DV32>
; __device__ __forceinline__ void pv_sub(f32x16 (&o)[DV32], const LAS unsigned char* Vt, int vs, int sub, const f32x16& p, int r32, int hi) {
;     ...
;     for (int kb = 0; kb < 2; ++kb) {
;         u32x4 pw; pw.x = cvt_pk_bf16(p[8 * kb + 0], p[8 * kb + 1]); pw.y = cvt_pk_bf16(p[8 * kb + 2], p[8 * kb + 3]); pw.z = cvt_pk_bf16(p[8 * kb + 4], p[8 * kb + 5]); pw.w = cvt_pk_bf16(p[8 * kb + 6], p[8 * kb + 7]);
;         const bf16x8 pf = __builtin_bit_cast(bf16x8, pw);
; #pragma unroll
;         for (int i = 0; i < DV32; ++i) {
;             const bf16x8 vf = *(const LAS bf16x8*)(Vt + (32 * i + r32) * vs + sub * 64 + kb * 32 + hi * 16);
;             o[i] = __builtin_amdgcn_mfma_f32_32x32x16_bf16(vf, pf, o[i], 0, 0, 0);
;         }
; template <int D, int DV, int MODE, bool HASBIAS, bool JOINT, bool DEFER, class KA, class VA, class PF, class BF, class VF, class NM, class WS, class CB> ...
;     ...
;                     l += sum; m = mn;
;                     if (MODE == 0) pv_sub<DV / 32>(o, curv, VS, sub, s, r32, hi);
.LBB0_323:
	v_cvt_pk_bf16_f32 v82, v16, v1
	v_cvt_pk_bf16_f32 v83, v2, v17
	v_add_f32_e32 v176, 0, v16
	v_add_f32_e32 v176, v1, v176
	v_add_f32_e32 v176, v2, v176
	v_add_f32_e32 v176, v17, v176
	v_add_u32_e32 v1, v217, v218
	ds_read_b128 v[90:93], v1 offset:34816
	ds_read_b128 v[94:97], v1 offset:39424
	v_cvt_pk_bf16_f32 v84, v4, v5
	v_cvt_pk_bf16_f32 v85, v6, v7
	v_add_f32_e32 v176, v4, v176
	v_add_f32_e32 v176, v5, v176
	s_waitcnt lgkmcnt(1)
	v_mfma_f32_32x32x16_bf16 v[66:81], v[90:93], v[82:85], v[66:81]
	ds_read_b128 v[90:93], v1 offset:44032
	v_add_f32_e32 v176, v6, v176
	v_add_f32_e32 v176, v7, v176
	v_cvt_pk_bf16_f32 v86, v8, v9
	v_cvt_pk_bf16_f32 v87, v10, v11
	s_waitcnt lgkmcnt(1)
	v_mfma_f32_32x32x16_bf16 v[50:65], v[94:97], v[82:85], v[50:65]
	ds_read_b128 v[94:97], v1 offset:48640
	v_add_f32_e32 v176, v8, v176
	v_add_f32_e32 v176, v9, v176
	v_add_f32_e32 v176, v10, v176
	v_add_f32_e32 v176, v11, v176
	s_waitcnt lgkmcnt(1)
	v_mfma_f32_32x32x16_bf16 v[34:49], v[90:93], v[82:85], v[34:49]
	ds_read_b128 v[90:93], v1 offset:34848
	v_cvt_pk_bf16_f32 v88, v12, v13
	v_cvt_pk_bf16_f32 v89, v14, v15
	v_add_f32_e32 v176, v12, v176
	v_add_f32_e32 v176, v13, v176
	s_waitcnt lgkmcnt(1)
	v_mfma_f32_32x32x16_bf16 v[18:33], v[94:97], v[82:85], v[18:33]
	ds_read_b128 v[94:97], v1 offset:39456
	v_add_f32_e32 v176, v14, v176
	v_add_f32_e32 v242, v15, v176
	v_add_f32_e32 v215, v242, v215
	s_waitcnt lgkmcnt(1)
	v_mfma_f32_32x32x16_bf16 v[66:81], v[90:93], v[86:89], v[66:81]
	ds_read_b128 v[90:93], v1 offset:44064
	s_waitcnt lgkmcnt(1)
	v_mfma_f32_32x32x16_bf16 v[50:65], v[94:97], v[86:89], v[50:65]
	ds_read_b128 v[94:97], v1 offset:48672
	s_waitcnt lgkmcnt(1)
	v_mfma_f32_32x32x16_bf16 v[34:49], v[90:93], v[86:89], v[34:49]
	s_waitcnt lgkmcnt(0)
	v_mfma_f32_32x32x16_bf16 v[18:33], v[94:97], v[86:89], v[18:33]
	s_branch .LBB0_325

; __device__ __forceinline__ float fast_exp2(float x) { return __builtin_amdgcn_exp2f(x); }
; __device__ __forceinline__ float xhalf_max(float x) { auto rr = __builtin_amdgcn_permlane32_swap(__float_as_uint(x), __float_as_uint(x), false, false); return fmaxf(__uint_as_float(rr[0]), __uint_as_float(rr[1])); }
; template <int D, int DV, int MODE, bool HASBIAS, bool JOINT, bool DEFER, class KA, class VA, class PF, class BF, class VF, class NM, class WS, class CB> ...
;     ...
;                     float mx0 = fmaxf(fmaxf(s[0], s[1]), s[2]), mx1 = fmaxf(fmaxf(s[3], s[4]), s[5]);
;                     mx0 = fmaxf(fmaxf(mx0, s[6]), s[7]); mx1 = fmaxf(fmaxf(mx1, s[8]), s[9]); mx0 = fmaxf(fmaxf(mx0, s[10]), s[11]); mx1 = fmaxf(fmaxf(mx1, s[12]), s[13]);
;                     float mx = fmaxf(fmaxf(mx0, mx1), fmaxf(s[14], s[15]));
;                     mx = xhalf_max(mx);
;                     const bool grow = __any(mx > m + RESC_THR);
;                     const float mn = grow ? fmaxf(m, mx) : m; float sum = 0.f;
;                     if (masked) {
; #pragma unroll
;                         for (int v = 0; v < 16; ++v) { const float p = s[v] > -1e29f ? fast_exp2(s[v] - mn) : 0.f; s[v] = p; sum += p; }
;                     } else {
; #pragma unroll
;                         for (int v = 0; v < 16; ++v) { const float p = fast_exp2(s[v] - mn); s[v] = p; sum += p; }
;                     }
.LBB0_328:
	v_max3_f32 v1, v82, v83, v96
	v_max3_f32 v2, v97, v86, v87
	v_max3_f32 v1, v1, v88, v89
	v_max3_f32 v2, v2, v90, v91
	v_max_f32_e32 v4, v85, v85
	v_max_f32_e32 v5, v84, v84
	v_max3_f32 v1, v1, v92, v93
	v_max3_f32 v2, v2, v94, v95
	v_max_f32_e32 v4, v5, v4
	v_max3_f32 v1, v1, v2, v4
	v_mov_b32_e32 v2, v1
	s_nop 1
	v_permlane32_swap_b32_e32 v1, v2
	v_max_f32_e32 v2, v2, v2
	v_max_f32_e32 v1, v1, v1
	v_max_f32_e32 v1, v1, v2
	v_add_f32_e32 v2, 0x40c00000, v233
	v_cmp_gt_f32_e32 vcc, v1, v2
	s_cmp_lg_u64 vcc, 0
	s_cselect_b64 s[8:9], -1, 0
	s_cmp_eq_u64 vcc, 0
	v_max_f32_e32 v2, v233, v233
	s_cselect_b64 vcc, -1, 0
	v_max_f32_e32 v234, v2, v1
	v_cndmask_b32_e32 v232, v234, v233, vcc
	v_sub_f32_e32 v1, v82, v232
	v_sub_f32_e32 v2, v83, v232
	v_sub_f32_e32 v4, v96, v232
	v_sub_f32_e32 v5, v97, v232
	v_sub_f32_e32 v6, v86, v232
	v_sub_f32_e32 v7, v87, v232
	v_sub_f32_e32 v8, v88, v232
	v_sub_f32_e32 v9, v89, v232
	v_sub_f32_e32 v10, v90, v232
	v_sub_f32_e32 v11, v91, v232
	v_sub_f32_e32 v12, v92, v232
	v_sub_f32_e32 v13, v93, v232
	v_sub_f32_e32 v14, v94, v232
	v_sub_f32_e32 v15, v95, v232
	v_sub_f32_e32 v176, v84, v232
	v_sub_f32_e32 v177, v85, v232
	v_exp_f32_e32 v16, v1
	v_exp_f32_e32 v1, v2
	v_exp_f32_e32 v2, v4
	v_exp_f32_e32 v17, v5
	v_exp_f32_e32 v4, v6
	v_exp_f32_e32 v5, v7
	v_exp_f32_e32 v6, v8
	v_exp_f32_e32 v7, v9
	v_exp_f32_e32 v8, v10
	v_exp_f32_e32 v9, v11
	v_exp_f32_e32 v10, v12
	v_exp_f32_e32 v11, v13
	v_exp_f32_e32 v12, v14
	v_exp_f32_e32 v13, v15
	v_exp_f32_e32 v14, v176
	v_exp_f32_e32 v15, v177
	s_mov_b64 s[16:17], -1
	s_andn2_b64 vcc, exec, s[10:11]
	s_cbranch_vccnz .LBB0_361
	s_cbranch_execz .LBB0_362

; __device__ __forceinline__ unsigned cvt_pk_bf16(float lo, float hi) { unsigned r; asm volatile("v_cvt_pk_bf16_f32 %0, %1, %2" : "=v"(r) : "v"(lo), "v"(hi)); return r; }
; #define LAS __attribute__((address_space(3)))
; template <int DV32>
; __device__ __forceinline__ void pv_sub(f32x16 (&o)[DV32], const LAS unsigned char* Vt, int vs, int sub, const f32x16& p, int r32, int hi) {
;     ...
;     for (int kb = 0; kb < 2; ++kb) {
;         u32x4 pw; pw.x = cvt_pk_bf16(p[8 * kb + 0], p[8 * kb + 1]); pw.y = cvt_pk_bf16(p[8 * kb + 2], p[8 * kb + 3]); pw.z = cvt_pk_bf16(p[8 * kb + 4], p[8 * kb + 5]); pw.w = cvt_pk_bf16(p[8 * kb + 6], p[8 * kb + 7]);
;         const bf16x8 pf = __builtin_bit_cast(bf16x8, pw);
; #pragma unroll
;         for (int i = 0; i < DV32; ++i) {
;             const bf16x8 vf = *(const LAS bf16x8*)(Vt + (32 * i + r32) * vs + sub * 64 + kb * 32 + hi * 16);
;             o[i] = __builtin_amdgcn_mfma_f32_32x32x16_bf16(vf, pf, o[i], 0, 0, 0);
;         }
; template <int D, int DV, int MODE, bool HASBIAS, bool JOINT, bool DEFER, class KA, class VA, class PF, class BF, class VF, class NM, class WS, class CB> ...
;     ...
;                     l += sum; m = mn;
;                     if (MODE == 0) pv_sub<DV / 32>(o, curv, VS, sub, s, r32, hi);
.LBB0_332:
	v_cvt_pk_bf16_f32 v82, v16, v1
	v_cvt_pk_bf16_f32 v83, v2, v17
	v_add_f32_e32 v176, 0, v16
	v_add_f32_e32 v176, v1, v176
	v_add_f32_e32 v176, v2, v176
	v_add_f32_e32 v176, v17, v176
	v_add_u32_e32 v1, v217, v218
	ds_read_b128 v[90:93], v1 offset:34880
	ds_read_b128 v[94:97], v1 offset:39488
	v_cvt_pk_bf16_f32 v84, v4, v5
	v_cvt_pk_bf16_f32 v85, v6, v7
	v_add_f32_e32 v176, v4, v176
	v_add_f32_e32 v176, v5, v176
	s_waitcnt lgkmcnt(1)
	v_mfma_f32_32x32x16_bf16 v[66:81], v[90:93], v[82:85], v[66:81]
	ds_read_b128 v[90:93], v1 offset:44096
	v_add_f32_e32 v176, v6, v176
	v_add_f32_e32 v176, v7, v176
	v_cvt_pk_bf16_f32 v86, v8, v9
	v_cvt_pk_bf16_f32 v87, v10, v11
	s_waitcnt lgkmcnt(1)
	v_mfma_f32_32x32x16_bf16 v[50:65], v[94:97], v[82:85], v[50:65]
	ds_read_b128 v[94:97], v1 offset:48704
	v_add_f32_e32 v176, v8, v176
	v_add_f32_e32 v176, v9, v176
	v_add_f32_e32 v176, v10, v176
	v_add_f32_e32 v176, v11, v176
	s_waitcnt lgkmcnt(1)
	v_mfma_f32_32x32x16_bf16 v[34:49], v[90:93], v[82:85], v[34:49]
	ds_read_b128 v[90:93], v1 offset:34912
	v_cvt_pk_bf16_f32 v88, v12, v13
	v_cvt_pk_bf16_f32 v89, v14, v15
	v_add_f32_e32 v176, v12, v176
	v_add_f32_e32 v176, v13, v176
	s_waitcnt lgkmcnt(1)
	v_mfma_f32_32x32x16_bf16 v[18:33], v[94:97], v[82:85], v[18:33]
	ds_read_b128 v[94:97], v1 offset:39520
	v_add_f32_e32 v176, v14, v176
	v_add_f32_e32 v242, v15, v176
	v_add_f32_e32 v215, v242, v215
	s_waitcnt lgkmcnt(1)
	v_mfma_f32_32x32x16_bf16 v[66:81], v[90:93], v[86:89], v[66:81]
	ds_read_b128 v[90:93], v1 offset:44128
	s_waitcnt lgkmcnt(1)
	v_mfma_f32_32x32x16_bf16 v[50:65], v[94:97], v[86:89], v[50:65]
	ds_read_b128 v[94:97], v1 offset:48736
	s_waitcnt lgkmcnt(1)
	v_mfma_f32_32x32x16_bf16 v[34:49], v[90:93], v[86:89], v[34:49]
	s_waitcnt lgkmcnt(0)
	v_mfma_f32_32x32x16_bf16 v[18:33], v[94:97], v[86:89], v[18:33]
	s_branch .LBB0_336

; __device__ __forceinline__ float fast_exp2(float x) { return __builtin_amdgcn_exp2f(x); }
; template <int D, int DV, int MODE, bool HASBIAS, bool JOINT, bool DEFER, class KA, class VA, class PF, class BF, class VF, class NM, class WS, class CB> ...
;     ...
;                     if (masked) {
; #pragma unroll
;                         for (int v = 0; v < 16; ++v) { const float p = s[v] > -1e29f ? fast_exp2(s[v] - mn) : 0.f; s[v] = p; sum += p; }
.LBB0_334:
	s_mov_b32 s10, 0xefa18f08
	v_cmp_lt_f32_e32 vcc, s10, v82
	s_nop 1
	v_cndmask_b32_e32 v16, 0, v16, vcc
	v_cmp_lt_f32_e32 vcc, s10, v83
	s_nop 1
	v_cndmask_b32_e32 v1, 0, v1, vcc
	v_cmp_lt_f32_e32 vcc, s10, v96
	s_nop 1
	v_cndmask_b32_e32 v2, 0, v2, vcc
	v_cmp_lt_f32_e32 vcc, s10, v97
	s_nop 1
	v_cndmask_b32_e32 v17, 0, v17, vcc
	v_cmp_lt_f32_e32 vcc, s10, v86
	s_nop 1
	v_cndmask_b32_e32 v4, 0, v4, vcc
	v_cmp_lt_f32_e32 vcc, s10, v87
	s_nop 1
	v_cndmask_b32_e32 v5, 0, v5, vcc
	v_cmp_lt_f32_e32 vcc, s10, v88
	s_nop 1
	v_cndmask_b32_e32 v6, 0, v6, vcc
	v_cmp_lt_f32_e32 vcc, s10, v89
	s_nop 1
	v_cndmask_b32_e32 v7, 0, v7, vcc
	v_cmp_lt_f32_e32 vcc, s10, v90
	s_nop 1
	v_cndmask_b32_e32 v8, 0, v8, vcc
	v_cmp_lt_f32_e32 vcc, s10, v91
	s_nop 1
	v_cndmask_b32_e32 v9, 0, v9, vcc
	v_cmp_lt_f32_e32 vcc, s10, v92
	s_nop 1
	v_cndmask_b32_e32 v10, 0, v10, vcc
	v_cmp_lt_f32_e32 vcc, s10, v93
	s_nop 1
	v_cndmask_b32_e32 v11, 0, v11, vcc
	v_cmp_lt_f32_e32 vcc, s10, v94
	s_nop 1
	v_cndmask_b32_e32 v12, 0, v12, vcc
	v_cmp_lt_f32_e32 vcc, s10, v95
	s_nop 1
	v_cndmask_b32_e32 v13, 0, v13, vcc
	v_cmp_lt_f32_e32 vcc, s10, v84
	s_nop 1
	v_cndmask_b32_e32 v14, 0, v14, vcc
	v_cmp_lt_f32_e32 vcc, s10, v85
	s_nop 1
	v_cndmask_b32_e32 v15, 0, v15, vcc
	s_andn2_b64 vcc, exec, s[8:9]
	s_cbranch_vccz .LBB0_322
	s_branch .LBB0_323

; __device__ __forceinline__ unsigned cvt_pk_bf16(float lo, float hi) { unsigned r; asm volatile("v_cvt_pk_bf16_f32 %0, %1, %2" : "=v"(r) : "v"(lo), "v"(hi)); return r; }
; #define LAS __attribute__((address_space(3)))
; template <int DV32>
; __device__ __forceinline__ void pv_sub(f32x16 (&o)[DV32], const LAS unsigned char* Vt, int vs, int sub, const f32x16& p, int r32, int hi) {
;     ...
;     for (int kb = 0; kb < 2; ++kb) {
;         u32x4 pw; pw.x = cvt_pk_bf16(p[8 * kb + 0], p[8 * kb + 1]); pw.y = cvt_pk_bf16(p[8 * kb + 2], p[8 * kb + 3]); pw.z = cvt_pk_bf16(p[8 * kb + 4], p[8 * kb + 5]); pw.w = cvt_pk_bf16(p[8 * kb + 6], p[8 * kb + 7]);
;         const bf16x8 pf = __builtin_bit_cast(bf16x8, pw);
; #pragma unroll
;         for (int i = 0; i < DV32; ++i) {
;             const bf16x8 vf = *(const LAS bf16x8*)(Vt + (32 * i + r32) * vs + sub * 64 + kb * 32 + hi * 16);
;             o[i] = __builtin_amdgcn_mfma_f32_32x32x16_bf16(vf, pf, o[i], 0, 0, 0);
;         }
; template <int D, int DV, int MODE, bool HASBIAS, bool JOINT, bool DEFER, class KA, class VA, class PF, class BF, class VF, class NM, class WS, class CB> ...
;     ...
;                     l += sum; m = mn;
;                     if (MODE == 0) pv_sub<DV / 32>(o, curv, VS, sub, s, r32, hi);
.LBB0_360:
	v_cvt_pk_bf16_f32 v82, v16, v1
	v_cvt_pk_bf16_f32 v83, v2, v17
	v_add_f32_e32 v176, 0, v16
	v_add_f32_e32 v176, v1, v176
	v_add_f32_e32 v176, v2, v176
	v_add_f32_e32 v176, v17, v176
	v_add_u32_e32 v1, v217, v218
	v_add_u32_e32 v2, v217, v219
	ds_read_b128 v[90:93], v1 offset:53248
	ds_read_b128 v[94:97], v1 offset:57856
	v_cvt_pk_bf16_f32 v84, v4, v5
	v_cvt_pk_bf16_f32 v85, v6, v7
	v_add_f32_e32 v176, v4, v176
	v_add_f32_e32 v176, v5, v176
	s_waitcnt lgkmcnt(1)
	v_mfma_f32_32x32x16_bf16 v[66:81], v[90:93], v[82:85], v[66:81]
	ds_read_b128 v[90:93], v1 offset:62464
	v_add_f32_e32 v176, v6, v176
	v_add_f32_e32 v176, v7, v176
	v_cvt_pk_bf16_f32 v86, v8, v9
	v_cvt_pk_bf16_f32 v87, v10, v11
	s_waitcnt lgkmcnt(1)
	v_mfma_f32_32x32x16_bf16 v[50:65], v[94:97], v[82:85], v[50:65]
	ds_read_b128 v[94:97], v2 offset:53248
	v_add_f32_e32 v176, v8, v176
	v_add_f32_e32 v176, v9, v176
	v_add_f32_e32 v176, v10, v176
	v_add_f32_e32 v176, v11, v176
	s_waitcnt lgkmcnt(1)
	v_mfma_f32_32x32x16_bf16 v[34:49], v[90:93], v[82:85], v[34:49]
	ds_read_b128 v[90:93], v1 offset:53280
	v_cvt_pk_bf16_f32 v88, v12, v13
	v_cvt_pk_bf16_f32 v89, v14, v15
	v_add_f32_e32 v176, v12, v176
	v_add_f32_e32 v176, v13, v176
	s_waitcnt lgkmcnt(1)
	v_mfma_f32_32x32x16_bf16 v[18:33], v[94:97], v[82:85], v[18:33]
	ds_read_b128 v[94:97], v1 offset:57888
	v_add_f32_e32 v176, v14, v176
	v_add_f32_e32 v242, v15, v176
	v_add_f32_e32 v215, v242, v215
	s_waitcnt lgkmcnt(1)
	v_mfma_f32_32x32x16_bf16 v[66:81], v[90:93], v[86:89], v[66:81]
	ds_read_b128 v[90:93], v1 offset:62496
	s_waitcnt lgkmcnt(1)
	v_mfma_f32_32x32x16_bf16 v[50:65], v[94:97], v[86:89], v[50:65]
	ds_read_b128 v[94:97], v2 offset:53280
	s_waitcnt lgkmcnt(1)
	v_mfma_f32_32x32x16_bf16 v[34:49], v[90:93], v[86:89], v[34:49]
	s_waitcnt lgkmcnt(0)
	v_mfma_f32_32x32x16_bf16 v[18:33], v[94:97], v[86:89], v[18:33]
	s_branch .LBB0_364

; __device__ __forceinline__ unsigned cvt_pk_bf16(float lo, float hi) { unsigned r; asm volatile("v_cvt_pk_bf16_f32 %0, %1, %2" : "=v"(r) : "v"(lo), "v"(hi)); return r; }
; #define LAS __attribute__((address_space(3)))
; template <int DV32>
; __device__ __forceinline__ void pv_sub(f32x16 (&o)[DV32], const LAS unsigned char* Vt, int vs, int sub, const f32x16& p, int r32, int hi) {
;     ...
;     for (int kb = 0; kb < 2; ++kb) {
;         u32x4 pw; pw.x = cvt_pk_bf16(p[8 * kb + 0], p[8 * kb + 1]); pw.y = cvt_pk_bf16(p[8 * kb + 2], p[8 * kb + 3]); pw.z = cvt_pk_bf16(p[8 * kb + 4], p[8 * kb + 5]); pw.w = cvt_pk_bf16(p[8 * kb + 6], p[8 * kb + 7]);
;         const bf16x8 pf = __builtin_bit_cast(bf16x8, pw);
; #pragma unroll
;         for (int i = 0; i < DV32; ++i) {
;             const bf16x8 vf = *(const LAS bf16x8*)(Vt + (32 * i + r32) * vs + sub * 64 + kb * 32 + hi * 16);
;             o[i] = __builtin_amdgcn_mfma_f32_32x32x16_bf16(vf, pf, o[i], 0, 0, 0);
;         }
; template <int D, int DV, int MODE, bool HASBIAS, bool JOINT, bool DEFER, class KA, class VA, class PF, class BF, class VF, class NM, class WS, class CB> ...
;     ...
;                     l += sum; m = mn;
;                     if (MODE == 0) pv_sub<DV / 32>(o, curv, VS, sub, s, r32, hi);
.LBB0_371:
	v_cvt_pk_bf16_f32 v82, v16, v1
	v_cvt_pk_bf16_f32 v83, v2, v17
	v_add_f32_e32 v176, 0, v16
	v_add_f32_e32 v176, v1, v176
	v_add_f32_e32 v176, v2, v176
	v_add_f32_e32 v176, v17, v176
	v_add_u32_e32 v1, v217, v218
	v_add_u32_e32 v2, v217, v219
	ds_read_b128 v[90:93], v1 offset:53312
	ds_read_b128 v[94:97], v1 offset:57920
	v_cvt_pk_bf16_f32 v84, v4, v5
	v_cvt_pk_bf16_f32 v85, v6, v7
	v_add_f32_e32 v176, v4, v176
	v_add_f32_e32 v176, v5, v176
	s_waitcnt lgkmcnt(1)
	v_mfma_f32_32x32x16_bf16 v[66:81], v[90:93], v[82:85], v[66:81]
	ds_read_b128 v[90:93], v1 offset:62528
	v_add_f32_e32 v176, v6, v176
	v_add_f32_e32 v176, v7, v176
	v_cvt_pk_bf16_f32 v86, v8, v9
	v_cvt_pk_bf16_f32 v87, v10, v11
	s_waitcnt lgkmcnt(1)
	v_mfma_f32_32x32x16_bf16 v[50:65], v[94:97], v[82:85], v[50:65]
	ds_read_b128 v[94:97], v2 offset:53312
	v_add_f32_e32 v176, v8, v176
	v_add_f32_e32 v176, v9, v176
	v_add_f32_e32 v176, v10, v176
	v_add_f32_e32 v176, v11, v176
	s_waitcnt lgkmcnt(1)
	v_mfma_f32_32x32x16_bf16 v[34:49], v[90:93], v[82:85], v[34:49]
	ds_read_b128 v[90:93], v1 offset:53344
	v_cvt_pk_bf16_f32 v88, v12, v13
	v_cvt_pk_bf16_f32 v89, v14, v15
	v_add_f32_e32 v176, v12, v176
	v_add_f32_e32 v176, v13, v176
	s_waitcnt lgkmcnt(1)
	v_mfma_f32_32x32x16_bf16 v[18:33], v[94:97], v[82:85], v[18:33]
	ds_read_b128 v[94:97], v1 offset:57952
	v_add_f32_e32 v176, v14, v176
	v_add_f32_e32 v242, v15, v176
	v_add_f32_e32 v215, v242, v215
	s_waitcnt lgkmcnt(1)
	v_mfma_f32_32x32x16_bf16 v[66:81], v[90:93], v[86:89], v[66:81]
	ds_read_b128 v[90:93], v1 offset:62560
	s_waitcnt lgkmcnt(1)
	v_mfma_f32_32x32x16_bf16 v[50:65], v[94:97], v[86:89], v[50:65]
	ds_read_b128 v[94:97], v2 offset:53344
	s_waitcnt lgkmcnt(1)
	v_mfma_f32_32x32x16_bf16 v[34:49], v[90:93], v[86:89], v[34:49]
	s_waitcnt lgkmcnt(0)
	v_mfma_f32_32x32x16_bf16 v[18:33], v[94:97], v[86:89], v[18:33]
	s_andn2_b64 vcc, exec, s[38:39]
	s_cbranch_vccnz .LBB0_306
	s_branch .LBB0_375
